# WIN band loop: first ring stage issued at SEL loop exit (behind an early barrier) so its DMA latency hides under the SEL-branch stash merge
# baseline (speedup 1.0000x reference)
; template <bool SEL> ...
;     ...
;     __syncthreads();
; #pragma unroll
;     for (int pi = 0; pi < 2; ++pi) if (pi < n) { const unsigned char* blk = KV + (size_t)(jhi - pi) * SLOTB; dma_block(lds3, pi, wu, blk, soff, blk + 8192, soff); }
; __device__ __forceinline__ void unitA(unsigned char* lds, PG8_LAS unsigned char* lds3, const Args& a, int b, int g, int T) {
;     ...
;         band_loop<false>(lds, lds3, (const unsigned char*)a.KVW + (size_t)bg * 128 * SLOTB, T, T - 8 > 0 ? T - 8 : 0, T, 512, q, tq, sw, H, farb, m, l, o, wu, soff, r, fq);
.LBB0_2649:
	s_barrier
	s_cmp_lt_i32 s0, 0
	s_cbranch_scc1 .Lwin_pf_done
	s_add_u32 s98, s73, s42
	s_addc_u32 s99, s74, 0
	s_lshl_b32 s100, s0, 14
	s_add_u32 s100, s98, s100
	s_addc_u32 s101, s99, 0
	v_lshl_add_u64 v[232:233], s[100:101], 0, v[0:1]
	s_mov_b32 s100, 0xffffc000
	s_mov_b32 s101, -1
	v_lshl_add_u64 v[236:237], v[232:233], 0, s[100:101]
	s_mov_b64 s[100:101], 0x2000
	v_lshl_add_u64 v[234:235], v[232:233], 0, s[100:101]
	v_lshl_add_u64 v[238:239], v[236:237], 0, s[100:101]
	s_mov_b32 s98, m0
	s_mov_b32 m0, s95
	s_nop 0
	global_load_lds_dwordx4 v[232:233], off
	s_add_i32 m0, s95, 0x2000
	s_nop 0
	global_load_lds_dwordx4 v[234:235], off
	s_cmp_lt_i32 s0, 1
	s_cbranch_scc1 .Lwin_pf_one
	s_add_i32 m0, s95, 0x4000
	s_nop 0
	global_load_lds_dwordx4 v[236:237], off
	s_add_i32 m0, s95, 0x6000
	s_nop 0
	global_load_lds_dwordx4 v[238:239], off

; #define GATE(br, cg_) fsigmoid(gatev[br][cg_])
; template <bool SEL> ...
;     ...
;     __syncthreads();
; #pragma unroll
;     for (int pi = 0; pi < 2; ++pi) if (pi < n) { const unsigned char* blk = KV + (size_t)(jhi - pi) * SLOTB; dma_block(lds3, pi, wu, blk, soff, blk + 8192, soff); }
; __device__ __forceinline__ void unitA(unsigned char* lds, PG8_LAS unsigned char* lds3, const Args& a, int b, int g, int T) {
;     ...
;         if (rep_ == REP_SEL - 1)
; #pragma unroll
;         for (int cg_ = 0; cg_ < 2; ++cg_) { const float sc = GATE(1, cg_) / quad_sum(l[cg_]);
; #pragma unroll
;             for (int df = 0; df < 4; ++df) stash[(cg_ * 4 + df) * 512 + tid] += o[cg_][df] * sc; }
.Lwin_pf_done:
	v_mul_f32_e32 v32, 0xbfb8aa3b, v139
	v_exp_f32_e32 v32, v32
	v_mov_b32_e32 v33, v127
	s_nop 1
	v_permlane16_swap_b32_e32 v127, v33
	v_add_f32_e32 v32, 1.0, v32
	v_rcp_f32_e32 v32, v32
	v_add_f32_e32 v33, v127, v33
	v_mov_b32_e32 v34, v33
	s_nop 1
	v_permlane32_swap_b32_e32 v33, v34
	v_add_f32_e32 v33, v33, v34
	v_div_scale_f32 v34, s[6:7], v33, v33, v32
	v_rcp_f32_e32 v35, v34
	s_add_u32 s34, s73, s42
	s_addc_u32 s35, s74, 0
	v_fma_f32 v36, -v34, v35, 1.0
	v_fmac_f32_e32 v35, v36, v35
	v_div_scale_f32 v36, vcc, v32, v33, v32
	v_mul_f32_e32 v37, v36, v35
	v_fma_f32 v38, -v34, v37, v36
	v_fmac_f32_e32 v37, v38, v35
	v_fma_f32 v34, -v34, v37, v36
	v_div_fmas_f32 v34, v34, v35, v37
	v_div_fixup_f32 v36, v34, v33, v32
	ds_read_b128 v[32:35], v178
	s_waitcnt lgkmcnt(0)
	v_pk_fma_f32 v[34:35], v[58:59], v[36:37], v[34:35] op_sel_hi:[1,0,1]
	v_pk_fma_f32 v[32:33], v[56:57], v[36:37], v[32:33] op_sel_hi:[1,0,1]
	ds_write_b128 v178, v[32:35]
	ds_read_b128 v[32:35], v178 offset:8192
	s_waitcnt lgkmcnt(0)
	v_pk_fma_f32 v[34:35], v[54:55], v[36:37], v[34:35] op_sel_hi:[1,0,1]
	v_pk_fma_f32 v[32:33], v[52:53], v[36:37], v[32:33] op_sel_hi:[1,0,1]
	ds_write_b128 v178, v[32:35] offset:8192
	ds_read_b128 v[32:35], v178 offset:16384
	s_waitcnt lgkmcnt(0)
	v_pk_fma_f32 v[34:35], v[50:51], v[36:37], v[34:35] op_sel_hi:[1,0,1]
	v_pk_fma_f32 v[32:33], v[48:49], v[36:37], v[32:33] op_sel_hi:[1,0,1]
	ds_write_b128 v178, v[32:35] offset:16384
	ds_read_b128 v[32:35], v178 offset:24576
	s_waitcnt lgkmcnt(0)
	v_pk_fma_f32 v[34:35], v[46:47], v[36:37], v[34:35] op_sel_hi:[1,0,1]
	v_pk_fma_f32 v[32:33], v[44:45], v[36:37], v[32:33] op_sel_hi:[1,0,1]
	ds_write_b128 v178, v[32:35] offset:24576
	v_mul_f32_e32 v32, 0xbfb8aa3b, v138
	v_exp_f32_e32 v32, v32
	v_mov_b32_e32 v33, v126
	s_nop 1
	v_permlane16_swap_b32_e32 v126, v33
	v_add_f32_e32 v32, 1.0, v32
	v_rcp_f32_e32 v32, v32
	v_add_f32_e32 v33, v126, v33
	v_mov_b32_e32 v34, v33
	s_nop 1
	v_permlane32_swap_b32_e32 v33, v34
	v_add_f32_e32 v33, v33, v34
	v_div_scale_f32 v34, s[6:7], v33, v33, v32
	v_rcp_f32_e32 v35, v34
	s_nop 0
	v_fma_f32 v36, -v34, v35, 1.0
	v_fmac_f32_e32 v35, v36, v35
	v_div_scale_f32 v36, vcc, v32, v33, v32
	v_mul_f32_e32 v37, v36, v35
	v_fma_f32 v38, -v34, v37, v36
	v_fmac_f32_e32 v37, v38, v35
	v_fma_f32 v34, -v34, v37, v36
	v_div_fmas_f32 v34, v34, v35, v37
	v_div_fixup_f32 v36, v34, v33, v32
	ds_read_b128 v[32:35], v178 offset:32768
	s_and_b64 vcc, exec, s[28:29]
	s_waitcnt lgkmcnt(0)
	v_pk_fma_f32 v[34:35], v[42:43], v[36:37], v[34:35] op_sel_hi:[1,0,1]
	v_pk_fma_f32 v[32:33], v[40:41], v[36:37], v[32:33] op_sel_hi:[1,0,1]
	ds_write_b128 v178, v[32:35] offset:32768
	ds_read_b128 v[32:35], v178 offset:40960
	s_waitcnt lgkmcnt(0)
	v_pk_fma_f32 v[30:31], v[30:31], v[36:37], v[34:35] op_sel_hi:[1,0,1]
	v_pk_fma_f32 v[28:29], v[28:29], v[36:37], v[32:33] op_sel_hi:[1,0,1]
	ds_write_b128 v178, v[28:31] offset:40960
	ds_read_b128 v[28:31], v178 offset:49152
	s_waitcnt lgkmcnt(0)
	v_pk_fma_f32 v[26:27], v[26:27], v[36:37], v[30:31] op_sel_hi:[1,0,1]
	v_pk_fma_f32 v[24:25], v[24:25], v[36:37], v[28:29] op_sel_hi:[1,0,1]
	ds_write_b128 v178, v[24:27] offset:49152
	ds_read_b128 v[24:27], v178 offset:57344
	s_waitcnt lgkmcnt(0)
	v_pk_fma_f32 v[22:23], v[22:23], v[36:37], v[26:27] op_sel_hi:[1,0,1]
	v_pk_fma_f32 v[20:21], v[20:21], v[36:37], v[24:25] op_sel_hi:[1,0,1]
	ds_write_b128 v178, v[20:23] offset:57344
	s_waitcnt lgkmcnt(0)
	s_barrier
	s_cbranch_vccz .LBB0_2652
	s_andn2_b64 vcc, exec, s[30:31]
	s_cbranch_vccz .LBB0_2653

; template <bool SEL> ...
;     ...
;     __syncthreads();
; #pragma unroll
;     for (int pi = 0; pi < 2; ++pi) if (pi < n) { const unsigned char* blk = KV + (size_t)(jhi - pi) * SLOTB; dma_block(lds3, pi, wu, blk, soff, blk + 8192, soff); }
;     for (int it0 = 0; it0 < n; it0 += 2) {
;         ring_wait_bar(0);
; __device__ __forceinline__ void unitA(unsigned char* lds, PG8_LAS unsigned char* lds3, const Args& a, int b, int g, int T) {
;     ...
;         float m[2] = {-1e30f, -1e30f}, l[2] = {0.f, 0.f}; f32x4 o[2][4];
; #pragma unroll
;         for (int cg_ = 0; cg_ < 2; ++cg_)
; #pragma unroll
;             for (int df = 0; df < 4; ++df) o[cg_][df] = (f32x4){0.f, 0.f, 0.f, 0.f};
;         band_loop<false>(lds, lds3, (const unsigned char*)a.KVW + (size_t)bg * 128 * SLOTB, T, T - 8 > 0 ? T - 8 : 0, T, 512, q, tq, sw, H, farb, m, l, o, wu, soff, r, fq);
.LBB0_2652:
	s_andn2_b64 vcc, exec, s[30:31]
	s_cbranch_vccnz .LBB0_2651
.LBB0_2653:
	s_and_b64 vcc, exec, s[28:29]
	s_cbranch_vccz .LBB0_2122
.LBB0_2654:
	v_lshlrev_b32_e32 v20, 7, v134
	v_lshl_or_b32 v20, v135, 10, v20
	v_or_b32_e32 v21, v20, v136
	v_or_b32_e32 v20, v20, v137
	v_mov_b32_e32 v22, v1
	v_mov_b32_e32 v23, v1
	s_min_i32 s1, s0, 8
	v_add_u32_e32 v180, 0, v21
	v_add_u32_e32 v181, 0, v20
	v_mov_b32_e32 v149, v148
	v_mov_b32_e32 v20, v1
	v_mov_b32_e32 v21, v1
	v_mov_b64_e32 v[30:31], v[22:23]
	v_mov_b64_e32 v[38:39], v[22:23]
	v_mov_b64_e32 v[46:47], v[22:23]
	v_mov_b64_e32 v[26:27], v[22:23]
	v_mov_b64_e32 v[34:35], v[22:23]
	v_mov_b64_e32 v[42:43], v[22:23]
	v_mov_b64_e32 v[50:51], v[22:23]
	v_mov_b32_e32 v154, v1
	v_mov_b32_e32 v155, v1
	s_mov_b32 s8, 0
	s_mov_b32 s28, 0
	s_movk_i32 s29, 0x200
	s_mov_b32 s30, s0
	v_mov_b64_e32 v[28:29], v[20:21]
	v_mov_b64_e32 v[36:37], v[20:21]
	v_mov_b64_e32 v[44:45], v[20:21]
	v_mov_b64_e32 v[24:25], v[20:21]
	v_mov_b64_e32 v[32:33], v[20:21]
	v_mov_b64_e32 v[40:41], v[20:21]
	v_mov_b64_e32 v[48:49], v[20:21]
	s_mov_b32 s31, s1
	v_mov_b64_e32 v[156:157], v[148:149]
